# snake order of the MFMAs inside each group of 8 in the P1/P9 K-loops (consecutive MFMAs share an operand), on top of bisection-count + P5 mask rewrites
# speedup vs baseline: 1.0061x; 1.0049x over previous
;     __host__ __device__ bool next(int i, Unit& u) const { const bool ok = StaticOrder::next(i >> 1, u); u.z = i & 1; return ok; }
; #define PG8_STAGE(bufoff, gbase, voff) do { _Pragma("unroll") for (int _i = 0; _i < 2; ++_i) \
;         __builtin_amdgcn_global_load_lds((const unsigned*)((const char*)(gbase) + (voff)[_i]), (LAS unsigned*)(lds + (bufoff) + ldsw + _i * 8192), 16, 0, 0); } while (0)
; #define PG8_LDA(dst, b, h) do { _Pragma("unroll") for (int m = 0; m < 4; ++m) _Pragma("unroll") for (int k = 0; k < 2; ++k) dst[m][k] = *(const LAS bf16x8*)(lds + PG8_SA(b, h) + aoff + m * 2048 + k * 1024); } while (0)
; #define PG8_LDB(dst, b, h) do { _Pragma("unroll") for (int n = 0; n < 2; ++n) _Pragma("unroll") for (int k = 0; k < 2; ++k) dst[n][k] = *(const LAS bf16x8*)(lds + PG8_SB(b, h) + boff + n * 2048 + k * 1024); } while (0)
; #define PG8_WAIT_V(n) asm volatile("s_waitcnt vmcnt(" #n ")" ::: "memory")
; #define PG8_WAIT_L(n) asm volatile("s_waitcnt lgkmcnt(" #n ")" ::: "memory")
; #define PG8_BAR __builtin_amdgcn_s_barrier()
; template <class Epi, class Sched, bool ALIGN_EPI = true, bool SP2 = true>
; __device__ __forceinline__ void gemm_phase(LAS unsigned char* lds, const Gemm g, const Sched& S, const Epi& E) {
;     ...
;         const bool has_next = S.next(ui + 1, nxt);
;         const char* nA = has_next ? PG8_ABASE(nxt) : cA; const char* nB = has_next ? PG8_BBASE(nxt) : cB;
;         for (int t = 0; t < nt; t += 2) {
;             const bool last = (t == nt - 2);
;             const char* a1 = cA + (size_t)(t + 1) * kstep;
;             const char* a2 = last ? nA : cA + (size_t)(t + 2) * kstep; const char* b2 = last ? nB : cB + (size_t)(t + 2) * kstep;
;             const char* a3 = a2 + kstep; const char* b3 = b2 + kstep;
;             if (last && has_next) S.a_ready(nxt);
;             if constexpr (SP2) {
;             PG8_LDB(B0, 0, 0); PG8_LDB(B1, 0, 1); PG8_SCHED; PG8_LDA(At, 0, 0); PG8_STAGE(PG8_SA(1, 1), a1 + hstep, voffA);
;             PG8_WAIT_V(8); PG8_WAIT_L(0); PG8_BAR; PG8_MMA(0, 0, At, B0); PG8_MMA(0, 1, At, B1); PG8_BAR; PG8_SCHED;
;             PG8_LDA(At, 0, 1); PG8_STAGE(PG8_SB(0, 0), b2, voffB); PG8_STAGE(PG8_SB(0, 1), b2 + hstep, voffB); PG8_STAGE(PG8_SA(0, 0), a2, voffA);
;             PG8_WAIT_V(8); PG8_WAIT_L(0); PG8_BAR; PG8_MMA(1, 0, At, B0); PG8_MMA(1, 1, At, B1); PG8_BAR; PG8_SCHED;
.LBB0_138:
	ds_read_b128 v[130:133], v170
	ds_read_b128 v[134:137], v170 offset:1024
	ds_read_b128 v[176:179], v170 offset:2048
	ds_read_b128 v[180:183], v170 offset:3072
	ds_read_b128 v[184:187], v171
	ds_read_b128 v[188:191], v171 offset:1024
	ds_read_b128 v[192:195], v171 offset:2048
	ds_read_b128 v[196:199], v171 offset:3072
	s_add_u32 s40, s38, 0xfff00080
	s_addc_u32 s41, s39, -1
	s_cmp_eq_u32 s66, 60
	s_cselect_b32 s43, s5, s41
	s_cselect_b32 s42, s18, s40
	s_cselect_b32 s41, s27, s65
	s_cselect_b32 s40, s29, s64
	v_lshl_add_u64 v[216:217], s[38:39], 0, v[152:153]
	s_add_i32 m0, s37, 0xc000
	ds_read_b128 v[200:203], v172
	ds_read_b128 v[204:207], v172 offset:1024
	ds_read_b128 v[208:211], v172 offset:2048
	ds_read_b128 v[212:215], v172 offset:3072
	ds_read_b128 v[220:223], v172 offset:4096
	ds_read_b128 v[224:227], v172 offset:5120
	ds_read_b128 v[228:231], v172 offset:6144
	ds_read_b128 v[232:235], v172 offset:7168
	global_load_lds_dwordx4 v[216:217], off
	v_lshl_add_u64 v[216:217], s[38:39], 0, v[154:155]
	s_add_i32 m0, s37, 0xe000
	s_nop 0
	global_load_lds_dwordx4 v[216:217], off
	s_waitcnt vmcnt(8)
	s_waitcnt lgkmcnt(0)
	s_barrier
	s_setprio 1
	s_waitcnt lgkmcnt(0)
	v_mfma_f32_16x16x32_bf16 v[126:129], v[130:133], v[200:203], v[126:129]
	v_mfma_f32_16x16x32_bf16 v[122:125], v[176:179], v[200:203], v[122:125]
	v_mfma_f32_16x16x32_bf16 v[106:109], v[176:179], v[208:211], v[106:109]
	v_mfma_f32_16x16x32_bf16 v[110:113], v[130:133], v[208:211], v[110:113]
	v_mfma_f32_16x16x32_bf16 v[94:97], v[130:133], v[220:223], v[94:97]
	v_mfma_f32_16x16x32_bf16 v[90:93], v[176:179], v[220:223], v[90:93]
	v_mfma_f32_16x16x32_bf16 v[74:77], v[176:179], v[228:231], v[74:77]
	v_mfma_f32_16x16x32_bf16 v[78:81], v[130:133], v[228:231], v[78:81]
	v_mfma_f32_16x16x32_bf16 v[126:129], v[134:137], v[204:207], v[126:129]
	v_mfma_f32_16x16x32_bf16 v[122:125], v[180:183], v[204:207], v[122:125]
	v_mfma_f32_16x16x32_bf16 v[106:109], v[180:183], v[212:215], v[106:109]
	v_mfma_f32_16x16x32_bf16 v[110:113], v[134:137], v[212:215], v[110:113]
	v_mfma_f32_16x16x32_bf16 v[94:97], v[134:137], v[224:227], v[94:97]
	v_mfma_f32_16x16x32_bf16 v[90:93], v[180:183], v[224:227], v[90:93]
	v_mfma_f32_16x16x32_bf16 v[74:77], v[180:183], v[232:235], v[74:77]
	v_mfma_f32_16x16x32_bf16 v[78:81], v[134:137], v[232:235], v[78:81]
	s_setprio 0
	s_setprio 1
	v_mfma_f32_16x16x32_bf16 v[118:121], v[184:187], v[200:203], v[118:121]
	v_mfma_f32_16x16x32_bf16 v[114:117], v[192:195], v[200:203], v[114:117]
	v_mfma_f32_16x16x32_bf16 v[98:101], v[192:195], v[208:211], v[98:101]
	v_mfma_f32_16x16x32_bf16 v[102:105], v[184:187], v[208:211], v[102:105]
	v_mfma_f32_16x16x32_bf16 v[86:89], v[184:187], v[220:223], v[86:89]
	v_mfma_f32_16x16x32_bf16 v[82:85], v[192:195], v[220:223], v[82:85]
	v_mfma_f32_16x16x32_bf16 v[66:69], v[192:195], v[228:231], v[66:69]
	v_mfma_f32_16x16x32_bf16 v[70:73], v[184:187], v[228:231], v[70:73]
	v_mfma_f32_16x16x32_bf16 v[118:121], v[188:191], v[204:207], v[118:121]
	v_mfma_f32_16x16x32_bf16 v[114:117], v[196:199], v[204:207], v[114:117]
	v_mfma_f32_16x16x32_bf16 v[98:101], v[196:199], v[212:215], v[98:101]
	v_mfma_f32_16x16x32_bf16 v[102:105], v[188:191], v[212:215], v[102:105]
	v_mfma_f32_16x16x32_bf16 v[86:89], v[188:191], v[224:227], v[86:89]
	v_mfma_f32_16x16x32_bf16 v[82:85], v[196:199], v[224:227], v[82:85]
	v_mfma_f32_16x16x32_bf16 v[66:69], v[196:199], v[232:235], v[66:69]
	v_mfma_f32_16x16x32_bf16 v[70:73], v[188:191], v[232:235], v[70:73]
	s_setprio 0
	s_barrier
	s_add_i32 s67, s60, s45
	v_lshl_add_u64 v[216:217], s[40:41], 0, v[140:141]
	s_mov_b32 m0, s67
	ds_read_b128 v[200:203], v172 offset:16384
	ds_read_b128 v[204:207], v172 offset:17408
	ds_read_b128 v[208:211], v172 offset:18432
	ds_read_b128 v[212:215], v172 offset:19456
	ds_read_b128 v[220:223], v172 offset:20480
	ds_read_b128 v[224:227], v172 offset:21504
	ds_read_b128 v[228:231], v172 offset:22528
	ds_read_b128 v[232:235], v172 offset:23552
	global_load_lds_dwordx4 v[216:217], off
	s_add_i32 m0, s67, 0x2000
	s_add_u32 s68, s40, 0x100000
	v_lshl_add_u64 v[218:219], s[40:41], 0, v[144:145]
	s_addc_u32 s69, s41, 0
	s_add_i32 s67, s61, s45
	global_load_lds_dwordx4 v[218:219], off
	v_lshl_add_u64 v[236:237], s[68:69], 0, v[140:141]
	s_mov_b32 m0, s67
	v_lshl_add_u64 v[238:239], s[42:43], 0, v[142:143]
	global_load_lds_dwordx4 v[236:237], off
	v_lshl_add_u64 v[236:237], s[68:69], 0, v[144:145]
	s_add_i32 m0, s67, 0x2000
	s_nop 0
	global_load_lds_dwordx4 v[236:237], off
	v_lshl_add_u64 v[236:237], s[42:43], 0, v[138:139]
	s_mov_b32 m0, s37
	s_nop 0
	global_load_lds_dwordx4 v[236:237], off
	s_mov_b32 m0, s47
	s_nop 0
	global_load_lds_dwordx4 v[238:239], off
	s_waitcnt vmcnt(8)
	s_waitcnt lgkmcnt(0)
	s_barrier
; #define PG8_STAGE(bufoff, gbase, voff) do { _Pragma("unroll") for (int _i = 0; _i < 2; ++_i) \
;         __builtin_amdgcn_global_load_lds((const unsigned*)((const char*)(gbase) + (voff)[_i]), (LAS unsigned*)(lds + (bufoff) + ldsw + _i * 8192), 16, 0, 0); } while (0)
; #define PG8_LDA(dst, b, h) do { _Pragma("unroll") for (int m = 0; m < 4; ++m) _Pragma("unroll") for (int k = 0; k < 2; ++k) dst[m][k] = *(const LAS bf16x8*)(lds + PG8_SA(b, h) + aoff + m * 2048 + k * 1024); } while (0)
; #define PG8_LDB(dst, b, h) do { _Pragma("unroll") for (int n = 0; n < 2; ++n) _Pragma("unroll") for (int k = 0; k < 2; ++k) dst[n][k] = *(const LAS bf16x8*)(lds + PG8_SB(b, h) + boff + n * 2048 + k * 1024); } while (0)
; #define PG8_MMA(ai, bj, At, Bt) do { __builtin_amdgcn_s_setprio(1); _Pragma("unroll") for (int m = 0; m < 4; ++m) _Pragma("unroll") for (int n = 0; n < 2; ++n) _Pragma("unroll") for (int k = 0; k < 2; ++k) \
;         acc[ai][bj][m][n] = __builtin_amdgcn_mfma_f32_16x16x32_bf16(Bt[n][k], At[m][k], acc[ai][bj][m][n], 0, 0, 0); __builtin_amdgcn_s_setprio(0); } while (0)
; #define PG8_WAIT_V(n) asm volatile("s_waitcnt vmcnt(" #n ")" ::: "memory")
; #define PG8_WAIT_L(n) asm volatile("s_waitcnt lgkmcnt(" #n ")" ::: "memory")
; #define PG8_BAR __builtin_amdgcn_s_barrier()
; #define PG8_SCHED __builtin_amdgcn_sched_barrier(0)
; template <class Epi, class Sched, bool ALIGN_EPI = true, bool SP2 = true>
; __device__ __forceinline__ void gemm_phase(LAS unsigned char* lds, const Gemm g, const Sched& S, const Epi& E) {
;     ...
;             PG8_WAIT_V(8); PG8_WAIT_L(0); PG8_BAR; PG8_MMA(1, 0, At, B0); PG8_MMA(1, 1, At, B1); PG8_BAR; PG8_SCHED;
;             PG8_LDB(B0, 1, 0); PG8_LDB(B1, 1, 1); PG8_SCHED; PG8_LDA(At, 1, 0); PG8_STAGE(PG8_SA(0, 1), a2 + hstep, voffA);
;             PG8_WAIT_V(8); PG8_WAIT_L(0); PG8_BAR; PG8_MMA(0, 0, At, B0); PG8_MMA(0, 1, At, B1); PG8_BAR; PG8_SCHED;
	s_setprio 1
	s_waitcnt lgkmcnt(0)
	v_mfma_f32_16x16x32_bf16 v[62:65], v[130:133], v[200:203], v[62:65]
	v_mfma_f32_16x16x32_bf16 v[58:61], v[176:179], v[200:203], v[58:61]
	v_mfma_f32_16x16x32_bf16 v[42:45], v[176:179], v[208:211], v[42:45]
	v_mfma_f32_16x16x32_bf16 v[46:49], v[130:133], v[208:211], v[46:49]
	v_mfma_f32_16x16x32_bf16 v[30:33], v[130:133], v[220:223], v[30:33]
	v_mfma_f32_16x16x32_bf16 v[26:29], v[176:179], v[220:223], v[26:29]
	v_mfma_f32_16x16x32_bf16 v[10:13], v[176:179], v[228:231], v[10:13]
	v_mfma_f32_16x16x32_bf16 v[14:17], v[130:133], v[228:231], v[14:17]
	v_mfma_f32_16x16x32_bf16 v[62:65], v[134:137], v[204:207], v[62:65]
	v_mfma_f32_16x16x32_bf16 v[58:61], v[180:183], v[204:207], v[58:61]
	v_mfma_f32_16x16x32_bf16 v[42:45], v[180:183], v[212:215], v[42:45]
	v_mfma_f32_16x16x32_bf16 v[46:49], v[134:137], v[212:215], v[46:49]
	v_mfma_f32_16x16x32_bf16 v[30:33], v[134:137], v[224:227], v[30:33]
	v_mfma_f32_16x16x32_bf16 v[26:29], v[180:183], v[224:227], v[26:29]
	v_mfma_f32_16x16x32_bf16 v[10:13], v[180:183], v[232:235], v[10:13]
	v_mfma_f32_16x16x32_bf16 v[14:17], v[134:137], v[232:235], v[14:17]
	s_setprio 0
	s_setprio 1
	v_mfma_f32_16x16x32_bf16 v[54:57], v[184:187], v[200:203], v[54:57]
	v_mfma_f32_16x16x32_bf16 v[50:53], v[192:195], v[200:203], v[50:53]
	v_mfma_f32_16x16x32_bf16 v[34:37], v[192:195], v[208:211], v[34:37]
	v_mfma_f32_16x16x32_bf16 v[38:41], v[184:187], v[208:211], v[38:41]
	v_mfma_f32_16x16x32_bf16 v[22:25], v[184:187], v[220:223], v[22:25]
	v_mfma_f32_16x16x32_bf16 v[18:21], v[192:195], v[220:223], v[18:21]
	v_mfma_f32_16x16x32_bf16 v[2:5], v[192:195], v[228:231], v[2:5]
	v_mfma_f32_16x16x32_bf16 v[6:9], v[184:187], v[228:231], v[6:9]
	v_mfma_f32_16x16x32_bf16 v[54:57], v[188:191], v[204:207], v[54:57]
	v_mfma_f32_16x16x32_bf16 v[50:53], v[196:199], v[204:207], v[50:53]
	v_mfma_f32_16x16x32_bf16 v[34:37], v[196:199], v[212:215], v[34:37]
	v_mfma_f32_16x16x32_bf16 v[38:41], v[188:191], v[212:215], v[38:41]
	v_mfma_f32_16x16x32_bf16 v[22:25], v[188:191], v[224:227], v[22:25]
	v_mfma_f32_16x16x32_bf16 v[18:21], v[196:199], v[224:227], v[18:21]
	v_mfma_f32_16x16x32_bf16 v[2:5], v[196:199], v[232:235], v[2:5]
	v_mfma_f32_16x16x32_bf16 v[6:9], v[188:191], v[232:235], v[6:9]
	s_setprio 0
	s_barrier
	s_add_i32 s67, 0, 0x18000
	v_add_u32_e32 v146, s67, v160
	s_add_i32 s68, 0, 0x1c000
	ds_read_b128 v[130:133], v146
	ds_read_b128 v[134:137], v146 offset:1024
	ds_read_b128 v[176:179], v146 offset:2048
	ds_read_b128 v[180:183], v146 offset:3072
	v_add_u32_e32 v146, s68, v160
	ds_read_b128 v[184:187], v146
	ds_read_b128 v[188:191], v146 offset:1024
	ds_read_b128 v[192:195], v146 offset:2048
	ds_read_b128 v[196:199], v146 offset:3072
	s_add_u32 s42, s42, 0x100000
	s_addc_u32 s43, s43, 0
	s_mov_b32 m0, s48
	v_lshl_add_u64 v[240:241], s[42:43], 0, v[138:139]
	ds_read_b128 v[200:203], v172 offset:32768
	ds_read_b128 v[204:207], v172 offset:33792
	ds_read_b128 v[208:211], v172 offset:34816
	ds_read_b128 v[212:215], v172 offset:35840
	ds_read_b128 v[220:223], v172 offset:36864
	ds_read_b128 v[224:227], v172 offset:37888
	ds_read_b128 v[228:231], v172 offset:38912
	ds_read_b128 v[232:235], v172 offset:39936
	global_load_lds_dwordx4 v[240:241], off
	v_lshl_add_u64 v[240:241], s[42:43], 0, v[142:143]
	s_mov_b32 m0, s49
	s_nop 0
	global_load_lds_dwordx4 v[240:241], off
	s_waitcnt vmcnt(8)
	s_waitcnt lgkmcnt(0)
	s_barrier
	s_setprio 1
	s_waitcnt lgkmcnt(0)
	v_mfma_f32_16x16x32_bf16 v[126:129], v[130:133], v[200:203], v[126:129]
	v_mfma_f32_16x16x32_bf16 v[122:125], v[176:179], v[200:203], v[122:125]
	v_mfma_f32_16x16x32_bf16 v[106:109], v[176:179], v[208:211], v[106:109]
	v_mfma_f32_16x16x32_bf16 v[110:113], v[130:133], v[208:211], v[110:113]
	v_mfma_f32_16x16x32_bf16 v[94:97], v[130:133], v[220:223], v[94:97]
	v_mfma_f32_16x16x32_bf16 v[90:93], v[176:179], v[220:223], v[90:93]
	v_mfma_f32_16x16x32_bf16 v[74:77], v[176:179], v[228:231], v[74:77]
	v_mfma_f32_16x16x32_bf16 v[78:81], v[130:133], v[228:231], v[78:81]
	v_mfma_f32_16x16x32_bf16 v[126:129], v[134:137], v[204:207], v[126:129]
	v_mfma_f32_16x16x32_bf16 v[122:125], v[180:183], v[204:207], v[122:125]
	v_mfma_f32_16x16x32_bf16 v[106:109], v[180:183], v[212:215], v[106:109]
	v_mfma_f32_16x16x32_bf16 v[110:113], v[134:137], v[212:215], v[110:113]
	v_mfma_f32_16x16x32_bf16 v[94:97], v[134:137], v[224:227], v[94:97]
	v_mfma_f32_16x16x32_bf16 v[90:93], v[180:183], v[224:227], v[90:93]
	v_mfma_f32_16x16x32_bf16 v[74:77], v[180:183], v[232:235], v[74:77]
	v_mfma_f32_16x16x32_bf16 v[78:81], v[134:137], v[232:235], v[78:81]
	s_setprio 0
	s_setprio 1
	v_mfma_f32_16x16x32_bf16 v[118:121], v[184:187], v[200:203], v[118:121]
	v_mfma_f32_16x16x32_bf16 v[114:117], v[192:195], v[200:203], v[114:117]
	v_mfma_f32_16x16x32_bf16 v[98:101], v[192:195], v[208:211], v[98:101]
	v_mfma_f32_16x16x32_bf16 v[102:105], v[184:187], v[208:211], v[102:105]
	v_mfma_f32_16x16x32_bf16 v[86:89], v[184:187], v[220:223], v[86:89]
	v_mfma_f32_16x16x32_bf16 v[82:85], v[192:195], v[220:223], v[82:85]
	v_mfma_f32_16x16x32_bf16 v[66:69], v[192:195], v[228:231], v[66:69]
	v_mfma_f32_16x16x32_bf16 v[70:73], v[184:187], v[228:231], v[70:73]
	v_mfma_f32_16x16x32_bf16 v[118:121], v[188:191], v[204:207], v[118:121]
	v_mfma_f32_16x16x32_bf16 v[114:117], v[196:199], v[204:207], v[114:117]
	v_mfma_f32_16x16x32_bf16 v[98:101], v[196:199], v[212:215], v[98:101]
	v_mfma_f32_16x16x32_bf16 v[102:105], v[188:191], v[212:215], v[102:105]
	v_mfma_f32_16x16x32_bf16 v[86:89], v[188:191], v[224:227], v[86:89]
	v_mfma_f32_16x16x32_bf16 v[82:85], v[196:199], v[224:227], v[82:85]
	v_mfma_f32_16x16x32_bf16 v[66:69], v[196:199], v[232:235], v[66:69]
	v_mfma_f32_16x16x32_bf16 v[70:73], v[188:191], v[232:235], v[70:73]
	s_setprio 0
	s_barrier
; #define PG8_STAGE(bufoff, gbase, voff) do { _Pragma("unroll") for (int _i = 0; _i < 2; ++_i) \
;         __builtin_amdgcn_global_load_lds((const unsigned*)((const char*)(gbase) + (voff)[_i]), (LAS unsigned*)(lds + (bufoff) + ldsw + _i * 8192), 16, 0, 0); } while (0)
; #define PG8_LDA(dst, b, h) do { _Pragma("unroll") for (int m = 0; m < 4; ++m) _Pragma("unroll") for (int k = 0; k < 2; ++k) dst[m][k] = *(const LAS bf16x8*)(lds + PG8_SA(b, h) + aoff + m * 2048 + k * 1024); } while (0)
; #define PG8_LDB(dst, b, h) do { _Pragma("unroll") for (int n = 0; n < 2; ++n) _Pragma("unroll") for (int k = 0; k < 2; ++k) dst[n][k] = *(const LAS bf16x8*)(lds + PG8_SB(b, h) + boff + n * 2048 + k * 1024); } while (0)
; template <class Epi, class Sched, bool ALIGN_EPI = true, bool SP2 = true>
; __device__ __forceinline__ void gemm_phase(LAS unsigned char* lds, const Gemm g, const Sched& S, const Epi& E) {
;     ...
;         for (int t = 0; t < nt; t += 2) {
;             const bool last = (t == nt - 2);
;             const char* a1 = cA + (size_t)(t + 1) * kstep;
;             const char* a2 = last ? nA : cA + (size_t)(t + 2) * kstep; const char* b2 = last ? nB : cB + (size_t)(t + 2) * kstep;
;             const char* a3 = a2 + kstep; const char* b3 = b2 + kstep;
;             if (last && has_next) S.a_ready(nxt);
;             if constexpr (SP2) {
;             PG8_LDB(B0, 0, 0); PG8_LDB(B1, 0, 1); PG8_SCHED; PG8_LDA(At, 0, 0); PG8_STAGE(PG8_SA(1, 1), a1 + hstep, voffA);
;             PG8_WAIT_V(8); PG8_WAIT_L(0); PG8_BAR; PG8_MMA(0, 0, At, B0); PG8_MMA(0, 1, At, B1); PG8_BAR; PG8_SCHED;
;             PG8_LDA(At, 0, 1); PG8_STAGE(PG8_SB(0, 0), b2, voffB); PG8_STAGE(PG8_SB(0, 1), b2 + hstep, voffB); PG8_STAGE(PG8_SA(0, 0), a2, voffA);
;             PG8_WAIT_V(8); PG8_WAIT_L(0); PG8_BAR; PG8_MMA(1, 0, At, B0); PG8_MMA(1, 1, At, B1); PG8_BAR; PG8_SCHED;
;             PG8_LDB(B0, 1, 0); PG8_LDB(B1, 1, 1); PG8_SCHED; PG8_LDA(At, 1, 0); PG8_STAGE(PG8_SA(0, 1), a2 + hstep, voffA);
;             PG8_WAIT_V(8); PG8_WAIT_L(0); PG8_BAR; PG8_MMA(0, 0, At, B0); PG8_MMA(0, 1, At, B1); PG8_BAR; PG8_SCHED;
;             PG8_LDA(At, 1, 1); PG8_STAGE(PG8_SB(1, 0), b3, voffB); PG8_STAGE(PG8_SB(1, 1), b3 + hstep, voffB); PG8_STAGE(PG8_SA(1, 0), a3, voffA);
;             PG8_WAIT_V(8); PG8_WAIT_L(0); PG8_BAR; PG8_MMA(1, 0, At, B0); PG8_MMA(1, 1, At, B1); PG8_BAR; PG8_SCHED;
	s_add_i32 s42, s67, s45
	v_lshl_add_u64 v[216:217], v[216:217], 0, s[22:23]
	s_mov_b32 m0, s42
	ds_read_b128 v[200:203], v172 offset:49152
	ds_read_b128 v[204:207], v172 offset:50176
	ds_read_b128 v[208:211], v172 offset:51200
	ds_read_b128 v[212:215], v172 offset:52224
	ds_read_b128 v[220:223], v172 offset:53248
	ds_read_b128 v[224:227], v172 offset:54272
	ds_read_b128 v[228:231], v172 offset:55296
	ds_read_b128 v[232:235], v172 offset:56320
	global_load_lds_dwordx4 v[216:217], off
	s_add_i32 m0, s42, 0x2000
	s_add_u32 s40, s40, 0x100080
	v_lshl_add_u64 v[216:217], v[218:219], 0, s[22:23]
	s_addc_u32 s41, s41, 0
	s_add_i32 s42, s68, s45
	global_load_lds_dwordx4 v[216:217], off
	v_lshl_add_u64 v[216:217], s[40:41], 0, v[140:141]
	s_mov_b32 m0, s42
	s_nop 0
	global_load_lds_dwordx4 v[216:217], off
	v_lshl_add_u64 v[216:217], s[40:41], 0, v[144:145]
	s_add_i32 m0, s42, 0x2000
	s_nop 0
	global_load_lds_dwordx4 v[216:217], off
	v_lshl_add_u64 v[216:217], v[236:237], 0, s[22:23]
	s_mov_b32 m0, s54
	s_nop 0
	global_load_lds_dwordx4 v[216:217], off
	v_lshl_add_u64 v[216:217], v[238:239], 0, s[22:23]
	s_mov_b32 m0, s55
	s_nop 0
	global_load_lds_dwordx4 v[216:217], off
	s_waitcnt vmcnt(8)
	s_waitcnt lgkmcnt(0)
	s_barrier
	s_setprio 1
	s_waitcnt lgkmcnt(0)
	v_mfma_f32_16x16x32_bf16 v[62:65], v[130:133], v[200:203], v[62:65]
	v_mfma_f32_16x16x32_bf16 v[58:61], v[176:179], v[200:203], v[58:61]
	v_mfma_f32_16x16x32_bf16 v[42:45], v[176:179], v[208:211], v[42:45]
	v_mfma_f32_16x16x32_bf16 v[46:49], v[130:133], v[208:211], v[46:49]
	v_mfma_f32_16x16x32_bf16 v[30:33], v[130:133], v[220:223], v[30:33]
	v_mfma_f32_16x16x32_bf16 v[26:29], v[176:179], v[220:223], v[26:29]
	v_mfma_f32_16x16x32_bf16 v[10:13], v[176:179], v[228:231], v[10:13]
	v_mfma_f32_16x16x32_bf16 v[14:17], v[130:133], v[228:231], v[14:17]
	v_mfma_f32_16x16x32_bf16 v[62:65], v[134:137], v[204:207], v[62:65]
	v_mfma_f32_16x16x32_bf16 v[58:61], v[180:183], v[204:207], v[58:61]
	v_mfma_f32_16x16x32_bf16 v[42:45], v[180:183], v[212:215], v[42:45]
	v_mfma_f32_16x16x32_bf16 v[46:49], v[134:137], v[212:215], v[46:49]
	v_mfma_f32_16x16x32_bf16 v[30:33], v[134:137], v[224:227], v[30:33]
	v_mfma_f32_16x16x32_bf16 v[26:29], v[180:183], v[224:227], v[26:29]
	v_mfma_f32_16x16x32_bf16 v[10:13], v[180:183], v[232:235], v[10:13]
	v_mfma_f32_16x16x32_bf16 v[14:17], v[134:137], v[232:235], v[14:17]
	s_setprio 0
	s_setprio 1
	v_mfma_f32_16x16x32_bf16 v[54:57], v[184:187], v[200:203], v[54:57]
	v_mfma_f32_16x16x32_bf16 v[50:53], v[192:195], v[200:203], v[50:53]
	v_mfma_f32_16x16x32_bf16 v[34:37], v[192:195], v[208:211], v[34:37]
	v_mfma_f32_16x16x32_bf16 v[38:41], v[184:187], v[208:211], v[38:41]
	v_mfma_f32_16x16x32_bf16 v[22:25], v[184:187], v[220:223], v[22:25]
	v_mfma_f32_16x16x32_bf16 v[18:21], v[192:195], v[220:223], v[18:21]
	v_mfma_f32_16x16x32_bf16 v[2:5], v[192:195], v[228:231], v[2:5]
	v_mfma_f32_16x16x32_bf16 v[6:9], v[184:187], v[228:231], v[6:9]
	v_mfma_f32_16x16x32_bf16 v[54:57], v[188:191], v[204:207], v[54:57]
	v_mfma_f32_16x16x32_bf16 v[50:53], v[196:199], v[204:207], v[50:53]
	v_mfma_f32_16x16x32_bf16 v[34:37], v[196:199], v[212:215], v[34:37]
	v_mfma_f32_16x16x32_bf16 v[38:41], v[188:191], v[212:215], v[38:41]
	v_mfma_f32_16x16x32_bf16 v[22:25], v[188:191], v[224:227], v[22:25]
	v_mfma_f32_16x16x32_bf16 v[18:21], v[196:199], v[224:227], v[18:21]
	v_mfma_f32_16x16x32_bf16 v[2:5], v[196:199], v[232:235], v[2:5]
	v_mfma_f32_16x16x32_bf16 v[6:9], v[188:191], v[232:235], v[6:9]
	s_setprio 0
	s_barrier
	s_add_i32 s66, s66, 2
	s_add_u32 s38, s38, 0x100
	s_addc_u32 s39, s39, 0
	s_add_u32 s64, s64, 0x100
	s_addc_u32 s65, s65, 0
	s_cmp_gt_u32 s66, 61
	s_cbranch_scc0 .LBB0_138
	s_and_b64 vcc, exec, s[24:25]
	s_cbranch_vccz .LBB0_141
	s_barrier

;     __host__ __device__ bool next(int i, Unit& u) const { const bool ok = StaticOrder::next(i >> 1, u); u.z = i & 1; return ok; }
; #define PG8_STAGE(bufoff, gbase, voff) do { _Pragma("unroll") for (int _i = 0; _i < 2; ++_i) \
;         __builtin_amdgcn_global_load_lds((const unsigned*)((const char*)(gbase) + (voff)[_i]), (LAS unsigned*)(lds + (bufoff) + ldsw + _i * 8192), 16, 0, 0); } while (0)
; #define PG8_LDA(dst, b, h) do { _Pragma("unroll") for (int m = 0; m < 4; ++m) _Pragma("unroll") for (int k = 0; k < 2; ++k) dst[m][k] = *(const LAS bf16x8*)(lds + PG8_SA(b, h) + aoff + m * 2048 + k * 1024); } while (0)
; #define PG8_LDB(dst, b, h) do { _Pragma("unroll") for (int n = 0; n < 2; ++n) _Pragma("unroll") for (int k = 0; k < 2; ++k) dst[n][k] = *(const LAS bf16x8*)(lds + PG8_SB(b, h) + boff + n * 2048 + k * 1024); } while (0)
; #define PG8_WAIT_V(n) asm volatile("s_waitcnt vmcnt(" #n ")" ::: "memory")
; #define PG8_WAIT_L(n) asm volatile("s_waitcnt lgkmcnt(" #n ")" ::: "memory")
; #define PG8_BAR __builtin_amdgcn_s_barrier()
; template <class Epi, class Sched, bool ALIGN_EPI = true, bool SP2 = true>
; __device__ __forceinline__ void gemm_phase(LAS unsigned char* lds, const Gemm g, const Sched& S, const Epi& E) {
;     ...
;         const bool has_next = S.next(ui + 1, nxt);
;         const char* nA = has_next ? PG8_ABASE(nxt) : cA; const char* nB = has_next ? PG8_BBASE(nxt) : cB;
;         for (int t = 0; t < nt; t += 2) {
;             const bool last = (t == nt - 2);
;             const char* a1 = cA + (size_t)(t + 1) * kstep;
;             const char* a2 = last ? nA : cA + (size_t)(t + 2) * kstep; const char* b2 = last ? nB : cB + (size_t)(t + 2) * kstep;
;             const char* a3 = a2 + kstep; const char* b3 = b2 + kstep;
;             if (last && has_next) S.a_ready(nxt);
;             if constexpr (SP2) {
;             PG8_LDB(B0, 0, 0); PG8_LDB(B1, 0, 1); PG8_SCHED; PG8_LDA(At, 0, 0); PG8_STAGE(PG8_SA(1, 1), a1 + hstep, voffA);
;             PG8_WAIT_V(8); PG8_WAIT_L(0); PG8_BAR; PG8_MMA(0, 0, At, B0); PG8_MMA(0, 1, At, B1); PG8_BAR; PG8_SCHED;
;             PG8_LDA(At, 0, 1); PG8_STAGE(PG8_SB(0, 0), b2, voffB); PG8_STAGE(PG8_SB(0, 1), b2 + hstep, voffB); PG8_STAGE(PG8_SA(0, 0), a2, voffA);
;             PG8_WAIT_V(8); PG8_WAIT_L(0); PG8_BAR; PG8_MMA(1, 0, At, B0); PG8_MMA(1, 1, At, B1); PG8_BAR; PG8_SCHED;
.LBB0_1810:
	ds_read_b128 v[148:151], v168
	ds_read_b128 v[152:155], v168 offset:1024
	ds_read_b128 v[156:159], v168 offset:2048
	ds_read_b128 v[160:163], v168 offset:3072
	ds_read_b128 v[174:177], v169
	ds_read_b128 v[178:181], v169 offset:1024
	ds_read_b128 v[182:185], v169 offset:2048
	ds_read_b128 v[186:189], v169 offset:3072
	s_add_u32 s30, s4, 0xfff00080
	s_addc_u32 s31, s5, -1
	s_cmp_eq_u32 s56, 60
	s_cselect_b32 s35, s25, s31
	s_cselect_b32 s34, s52, s30
	s_cselect_b32 s31, s23, s55
	s_cselect_b32 s30, s53, s54
	v_lshl_add_u64 v[164:165], s[4:5], 0, v[140:141]
	s_add_i32 m0, s40, 0xc000
	ds_read_b128 v[190:193], v170
	ds_read_b128 v[194:197], v170 offset:1024
	ds_read_b128 v[198:201], v170 offset:2048
	ds_read_b128 v[202:205], v170 offset:3072
	ds_read_b128 v[206:209], v170 offset:4096
	ds_read_b128 v[210:213], v170 offset:5120
	ds_read_b128 v[214:217], v170 offset:6144
	ds_read_b128 v[218:221], v170 offset:7168
	global_load_lds_dwordx4 v[164:165], off
	v_lshl_add_u64 v[164:165], s[4:5], 0, v[142:143]
	s_add_i32 m0, s40, 0xe000
	s_nop 0
	global_load_lds_dwordx4 v[164:165], off
	s_waitcnt vmcnt(8)
	s_waitcnt lgkmcnt(0)
	s_barrier
	s_setprio 1
	s_waitcnt lgkmcnt(0)
	v_mfma_f32_16x16x32_bf16 v[126:129], v[148:151], v[190:193], v[126:129]
	v_mfma_f32_16x16x32_bf16 v[122:125], v[156:159], v[190:193], v[122:125]
	v_mfma_f32_16x16x32_bf16 v[106:109], v[156:159], v[198:201], v[106:109]
	v_mfma_f32_16x16x32_bf16 v[110:113], v[148:151], v[198:201], v[110:113]
	v_mfma_f32_16x16x32_bf16 v[94:97], v[148:151], v[206:209], v[94:97]
	v_mfma_f32_16x16x32_bf16 v[90:93], v[156:159], v[206:209], v[90:93]
	v_mfma_f32_16x16x32_bf16 v[74:77], v[156:159], v[214:217], v[74:77]
	v_mfma_f32_16x16x32_bf16 v[78:81], v[148:151], v[214:217], v[78:81]
	v_mfma_f32_16x16x32_bf16 v[126:129], v[152:155], v[194:197], v[126:129]
	v_mfma_f32_16x16x32_bf16 v[122:125], v[160:163], v[194:197], v[122:125]
	v_mfma_f32_16x16x32_bf16 v[106:109], v[160:163], v[202:205], v[106:109]
	v_mfma_f32_16x16x32_bf16 v[110:113], v[152:155], v[202:205], v[110:113]
	v_mfma_f32_16x16x32_bf16 v[94:97], v[152:155], v[210:213], v[94:97]
	v_mfma_f32_16x16x32_bf16 v[90:93], v[160:163], v[210:213], v[90:93]
	v_mfma_f32_16x16x32_bf16 v[74:77], v[160:163], v[218:221], v[74:77]
	v_mfma_f32_16x16x32_bf16 v[78:81], v[152:155], v[218:221], v[78:81]
	s_setprio 0
	s_setprio 1
	v_mfma_f32_16x16x32_bf16 v[118:121], v[174:177], v[190:193], v[118:121]
	v_mfma_f32_16x16x32_bf16 v[114:117], v[182:185], v[190:193], v[114:117]
	v_mfma_f32_16x16x32_bf16 v[98:101], v[182:185], v[198:201], v[98:101]
	v_mfma_f32_16x16x32_bf16 v[102:105], v[174:177], v[198:201], v[102:105]
	v_mfma_f32_16x16x32_bf16 v[86:89], v[174:177], v[206:209], v[86:89]
	v_mfma_f32_16x16x32_bf16 v[82:85], v[182:185], v[206:209], v[82:85]
	v_mfma_f32_16x16x32_bf16 v[66:69], v[182:185], v[214:217], v[66:69]
	v_mfma_f32_16x16x32_bf16 v[70:73], v[174:177], v[214:217], v[70:73]
	v_mfma_f32_16x16x32_bf16 v[118:121], v[178:181], v[194:197], v[118:121]
	v_mfma_f32_16x16x32_bf16 v[114:117], v[186:189], v[194:197], v[114:117]
	v_mfma_f32_16x16x32_bf16 v[98:101], v[186:189], v[202:205], v[98:101]
	v_mfma_f32_16x16x32_bf16 v[102:105], v[178:181], v[202:205], v[102:105]
	v_mfma_f32_16x16x32_bf16 v[86:89], v[178:181], v[210:213], v[86:89]
	v_mfma_f32_16x16x32_bf16 v[82:85], v[186:189], v[210:213], v[82:85]
	v_mfma_f32_16x16x32_bf16 v[66:69], v[186:189], v[218:221], v[66:69]
	v_mfma_f32_16x16x32_bf16 v[70:73], v[178:181], v[218:221], v[70:73]
	s_setprio 0
	s_barrier
	s_add_i32 s57, s48, s37
	v_lshl_add_u64 v[164:165], s[30:31], 0, v[134:135]
	s_mov_b32 m0, s57
	ds_read_b128 v[190:193], v170 offset:16384
	ds_read_b128 v[194:197], v170 offset:17408
	ds_read_b128 v[198:201], v170 offset:18432
	ds_read_b128 v[202:205], v170 offset:19456
	ds_read_b128 v[206:209], v170 offset:20480
	ds_read_b128 v[210:213], v170 offset:21504
	ds_read_b128 v[214:217], v170 offset:22528
	ds_read_b128 v[218:221], v170 offset:23552
	global_load_lds_dwordx4 v[164:165], off
	s_add_i32 m0, s57, 0x2000
	s_add_u32 s58, s30, 0x100000
	v_lshl_add_u64 v[222:223], s[30:31], 0, v[130:131]
	s_addc_u32 s59, s31, 0
	s_add_i32 s57, s49, s37
	global_load_lds_dwordx4 v[222:223], off
	v_lshl_add_u64 v[224:225], s[58:59], 0, v[134:135]
	s_mov_b32 m0, s57
	v_lshl_add_u64 v[226:227], s[34:35], 0, v[132:133]
	global_load_lds_dwordx4 v[224:225], off
	v_lshl_add_u64 v[224:225], s[58:59], 0, v[130:131]
	s_add_i32 m0, s57, 0x2000
	s_nop 0
	global_load_lds_dwordx4 v[224:225], off
	v_lshl_add_u64 v[224:225], s[34:35], 0, v[136:137]
	s_mov_b32 m0, s40
	s_nop 0
	global_load_lds_dwordx4 v[224:225], off
	s_mov_b32 m0, s41
	s_nop 0
	global_load_lds_dwordx4 v[226:227], off
	s_waitcnt vmcnt(8)
	s_waitcnt lgkmcnt(0)
	s_barrier
; #define PG8_STAGE(bufoff, gbase, voff) do { _Pragma("unroll") for (int _i = 0; _i < 2; ++_i) \
;         __builtin_amdgcn_global_load_lds((const unsigned*)((const char*)(gbase) + (voff)[_i]), (LAS unsigned*)(lds + (bufoff) + ldsw + _i * 8192), 16, 0, 0); } while (0)
; #define PG8_LDA(dst, b, h) do { _Pragma("unroll") for (int m = 0; m < 4; ++m) _Pragma("unroll") for (int k = 0; k < 2; ++k) dst[m][k] = *(const LAS bf16x8*)(lds + PG8_SA(b, h) + aoff + m * 2048 + k * 1024); } while (0)
; #define PG8_LDB(dst, b, h) do { _Pragma("unroll") for (int n = 0; n < 2; ++n) _Pragma("unroll") for (int k = 0; k < 2; ++k) dst[n][k] = *(const LAS bf16x8*)(lds + PG8_SB(b, h) + boff + n * 2048 + k * 1024); } while (0)
; #define PG8_MMA(ai, bj, At, Bt) do { __builtin_amdgcn_s_setprio(1); _Pragma("unroll") for (int m = 0; m < 4; ++m) _Pragma("unroll") for (int n = 0; n < 2; ++n) _Pragma("unroll") for (int k = 0; k < 2; ++k) \
;         acc[ai][bj][m][n] = __builtin_amdgcn_mfma_f32_16x16x32_bf16(Bt[n][k], At[m][k], acc[ai][bj][m][n], 0, 0, 0); __builtin_amdgcn_s_setprio(0); } while (0)
; #define PG8_WAIT_V(n) asm volatile("s_waitcnt vmcnt(" #n ")" ::: "memory")
; #define PG8_WAIT_L(n) asm volatile("s_waitcnt lgkmcnt(" #n ")" ::: "memory")
; #define PG8_BAR __builtin_amdgcn_s_barrier()
; #define PG8_SCHED __builtin_amdgcn_sched_barrier(0)
; template <class Epi, class Sched, bool ALIGN_EPI = true, bool SP2 = true>
; __device__ __forceinline__ void gemm_phase(LAS unsigned char* lds, const Gemm g, const Sched& S, const Epi& E) {
;     ...
;             PG8_WAIT_V(8); PG8_WAIT_L(0); PG8_BAR; PG8_MMA(1, 0, At, B0); PG8_MMA(1, 1, At, B1); PG8_BAR; PG8_SCHED;
;             PG8_LDB(B0, 1, 0); PG8_LDB(B1, 1, 1); PG8_SCHED; PG8_LDA(At, 1, 0); PG8_STAGE(PG8_SA(0, 1), a2 + hstep, voffA);
;             PG8_WAIT_V(8); PG8_WAIT_L(0); PG8_BAR; PG8_MMA(0, 0, At, B0); PG8_MMA(0, 1, At, B1); PG8_BAR; PG8_SCHED;
	s_setprio 1
	s_waitcnt lgkmcnt(0)
	v_mfma_f32_16x16x32_bf16 v[62:65], v[148:151], v[190:193], v[62:65]
	v_mfma_f32_16x16x32_bf16 v[58:61], v[156:159], v[190:193], v[58:61]
	v_mfma_f32_16x16x32_bf16 v[42:45], v[156:159], v[198:201], v[42:45]
	v_mfma_f32_16x16x32_bf16 v[46:49], v[148:151], v[198:201], v[46:49]
	v_mfma_f32_16x16x32_bf16 v[30:33], v[148:151], v[206:209], v[30:33]
	v_mfma_f32_16x16x32_bf16 v[26:29], v[156:159], v[206:209], v[26:29]
	v_mfma_f32_16x16x32_bf16 v[10:13], v[156:159], v[214:217], v[10:13]
	v_mfma_f32_16x16x32_bf16 v[14:17], v[148:151], v[214:217], v[14:17]
	v_mfma_f32_16x16x32_bf16 v[62:65], v[152:155], v[194:197], v[62:65]
	v_mfma_f32_16x16x32_bf16 v[58:61], v[160:163], v[194:197], v[58:61]
	v_mfma_f32_16x16x32_bf16 v[42:45], v[160:163], v[202:205], v[42:45]
	v_mfma_f32_16x16x32_bf16 v[46:49], v[152:155], v[202:205], v[46:49]
	v_mfma_f32_16x16x32_bf16 v[30:33], v[152:155], v[210:213], v[30:33]
	v_mfma_f32_16x16x32_bf16 v[26:29], v[160:163], v[210:213], v[26:29]
	v_mfma_f32_16x16x32_bf16 v[10:13], v[160:163], v[218:221], v[10:13]
	v_mfma_f32_16x16x32_bf16 v[14:17], v[152:155], v[218:221], v[14:17]
	s_setprio 0
	s_setprio 1
	v_mfma_f32_16x16x32_bf16 v[54:57], v[174:177], v[190:193], v[54:57]
	v_mfma_f32_16x16x32_bf16 v[50:53], v[182:185], v[190:193], v[50:53]
	v_mfma_f32_16x16x32_bf16 v[34:37], v[182:185], v[198:201], v[34:37]
	v_mfma_f32_16x16x32_bf16 v[38:41], v[174:177], v[198:201], v[38:41]
	v_mfma_f32_16x16x32_bf16 v[22:25], v[174:177], v[206:209], v[22:25]
	v_mfma_f32_16x16x32_bf16 v[18:21], v[182:185], v[206:209], v[18:21]
	v_mfma_f32_16x16x32_bf16 v[2:5], v[182:185], v[214:217], v[2:5]
	v_mfma_f32_16x16x32_bf16 v[6:9], v[174:177], v[214:217], v[6:9]
	v_mfma_f32_16x16x32_bf16 v[54:57], v[178:181], v[194:197], v[54:57]
	v_mfma_f32_16x16x32_bf16 v[50:53], v[186:189], v[194:197], v[50:53]
	v_mfma_f32_16x16x32_bf16 v[34:37], v[186:189], v[202:205], v[34:37]
	v_mfma_f32_16x16x32_bf16 v[38:41], v[178:181], v[202:205], v[38:41]
	v_mfma_f32_16x16x32_bf16 v[22:25], v[178:181], v[210:213], v[22:25]
	v_mfma_f32_16x16x32_bf16 v[18:21], v[186:189], v[210:213], v[18:21]
	v_mfma_f32_16x16x32_bf16 v[2:5], v[186:189], v[218:221], v[2:5]
	v_mfma_f32_16x16x32_bf16 v[6:9], v[178:181], v[218:221], v[6:9]
	s_setprio 0
	s_barrier
	s_add_i32 s57, 0, 0x18000
	s_add_i32 s58, 0, 0x1c000
	v_add_u32_e32 v160, s57, v167
	v_add_u32_e32 v173, s58, v167
	ds_read_b128 v[148:151], v160
	ds_read_b128 v[152:155], v160 offset:1024
	ds_read_b128 v[156:159], v160 offset:2048
	ds_read_b128 v[160:163], v160 offset:3072
	ds_read_b128 v[174:177], v173
	ds_read_b128 v[178:181], v173 offset:1024
	ds_read_b128 v[182:185], v173 offset:2048
	ds_read_b128 v[186:189], v173 offset:3072
	s_add_u32 s34, s34, 0x100000
	s_addc_u32 s35, s35, 0
	s_mov_b32 m0, s42
	v_lshl_add_u64 v[228:229], s[34:35], 0, v[136:137]
	ds_read_b128 v[190:193], v170 offset:32768
	ds_read_b128 v[194:197], v170 offset:33792
	ds_read_b128 v[198:201], v170 offset:34816
	ds_read_b128 v[202:205], v170 offset:35840
	ds_read_b128 v[206:209], v170 offset:36864
	ds_read_b128 v[210:213], v170 offset:37888
	ds_read_b128 v[214:217], v170 offset:38912
	ds_read_b128 v[218:221], v170 offset:39936
	global_load_lds_dwordx4 v[228:229], off
	v_lshl_add_u64 v[228:229], s[34:35], 0, v[132:133]
	s_mov_b32 m0, s43
	s_nop 0
	global_load_lds_dwordx4 v[228:229], off
	s_waitcnt vmcnt(8)
	s_waitcnt lgkmcnt(0)
	s_barrier
	s_setprio 1
	s_waitcnt lgkmcnt(0)
	v_mfma_f32_16x16x32_bf16 v[126:129], v[148:151], v[190:193], v[126:129]
	v_mfma_f32_16x16x32_bf16 v[122:125], v[156:159], v[190:193], v[122:125]
	v_mfma_f32_16x16x32_bf16 v[106:109], v[156:159], v[198:201], v[106:109]
	v_mfma_f32_16x16x32_bf16 v[110:113], v[148:151], v[198:201], v[110:113]
	v_mfma_f32_16x16x32_bf16 v[94:97], v[148:151], v[206:209], v[94:97]
	v_mfma_f32_16x16x32_bf16 v[90:93], v[156:159], v[206:209], v[90:93]
	v_mfma_f32_16x16x32_bf16 v[74:77], v[156:159], v[214:217], v[74:77]
	v_mfma_f32_16x16x32_bf16 v[78:81], v[148:151], v[214:217], v[78:81]
	v_mfma_f32_16x16x32_bf16 v[126:129], v[152:155], v[194:197], v[126:129]
	v_mfma_f32_16x16x32_bf16 v[122:125], v[160:163], v[194:197], v[122:125]
	v_mfma_f32_16x16x32_bf16 v[106:109], v[160:163], v[202:205], v[106:109]
	v_mfma_f32_16x16x32_bf16 v[110:113], v[152:155], v[202:205], v[110:113]
	v_mfma_f32_16x16x32_bf16 v[94:97], v[152:155], v[210:213], v[94:97]
	v_mfma_f32_16x16x32_bf16 v[90:93], v[160:163], v[210:213], v[90:93]
	v_mfma_f32_16x16x32_bf16 v[74:77], v[160:163], v[218:221], v[74:77]
	v_mfma_f32_16x16x32_bf16 v[78:81], v[152:155], v[218:221], v[78:81]
	s_setprio 0
	s_setprio 1
	v_mfma_f32_16x16x32_bf16 v[118:121], v[174:177], v[190:193], v[118:121]
	v_mfma_f32_16x16x32_bf16 v[114:117], v[182:185], v[190:193], v[114:117]
	v_mfma_f32_16x16x32_bf16 v[98:101], v[182:185], v[198:201], v[98:101]
	v_mfma_f32_16x16x32_bf16 v[102:105], v[174:177], v[198:201], v[102:105]
	v_mfma_f32_16x16x32_bf16 v[86:89], v[174:177], v[206:209], v[86:89]
	v_mfma_f32_16x16x32_bf16 v[82:85], v[182:185], v[206:209], v[82:85]
	v_mfma_f32_16x16x32_bf16 v[66:69], v[182:185], v[214:217], v[66:69]
	v_mfma_f32_16x16x32_bf16 v[70:73], v[174:177], v[214:217], v[70:73]
	v_mfma_f32_16x16x32_bf16 v[118:121], v[178:181], v[194:197], v[118:121]
	v_mfma_f32_16x16x32_bf16 v[114:117], v[186:189], v[194:197], v[114:117]
	v_mfma_f32_16x16x32_bf16 v[98:101], v[186:189], v[202:205], v[98:101]
	v_mfma_f32_16x16x32_bf16 v[102:105], v[178:181], v[202:205], v[102:105]
	v_mfma_f32_16x16x32_bf16 v[86:89], v[178:181], v[210:213], v[86:89]
	v_mfma_f32_16x16x32_bf16 v[82:85], v[186:189], v[210:213], v[82:85]
	v_mfma_f32_16x16x32_bf16 v[66:69], v[186:189], v[218:221], v[66:69]
	v_mfma_f32_16x16x32_bf16 v[70:73], v[178:181], v[218:221], v[70:73]
	s_setprio 0
	s_barrier
; #define PG8_STAGE(bufoff, gbase, voff) do { _Pragma("unroll") for (int _i = 0; _i < 2; ++_i) \
;         __builtin_amdgcn_global_load_lds((const unsigned*)((const char*)(gbase) + (voff)[_i]), (LAS unsigned*)(lds + (bufoff) + ldsw + _i * 8192), 16, 0, 0); } while (0)
; #define PG8_LDA(dst, b, h) do { _Pragma("unroll") for (int m = 0; m < 4; ++m) _Pragma("unroll") for (int k = 0; k < 2; ++k) dst[m][k] = *(const LAS bf16x8*)(lds + PG8_SA(b, h) + aoff + m * 2048 + k * 1024); } while (0)
; #define PG8_LDB(dst, b, h) do { _Pragma("unroll") for (int n = 0; n < 2; ++n) _Pragma("unroll") for (int k = 0; k < 2; ++k) dst[n][k] = *(const LAS bf16x8*)(lds + PG8_SB(b, h) + boff + n * 2048 + k * 1024); } while (0)
; template <class Epi, class Sched, bool ALIGN_EPI = true, bool SP2 = true>
; __device__ __forceinline__ void gemm_phase(LAS unsigned char* lds, const Gemm g, const Sched& S, const Epi& E) {
;     ...
;         for (int t = 0; t < nt; t += 2) {
;             const bool last = (t == nt - 2);
;             const char* a1 = cA + (size_t)(t + 1) * kstep;
;             const char* a2 = last ? nA : cA + (size_t)(t + 2) * kstep; const char* b2 = last ? nB : cB + (size_t)(t + 2) * kstep;
;             const char* a3 = a2 + kstep; const char* b3 = b2 + kstep;
;             if (last && has_next) S.a_ready(nxt);
;             if constexpr (SP2) {
;             PG8_LDB(B0, 0, 0); PG8_LDB(B1, 0, 1); PG8_SCHED; PG8_LDA(At, 0, 0); PG8_STAGE(PG8_SA(1, 1), a1 + hstep, voffA);
;             PG8_WAIT_V(8); PG8_WAIT_L(0); PG8_BAR; PG8_MMA(0, 0, At, B0); PG8_MMA(0, 1, At, B1); PG8_BAR; PG8_SCHED;
;             PG8_LDA(At, 0, 1); PG8_STAGE(PG8_SB(0, 0), b2, voffB); PG8_STAGE(PG8_SB(0, 1), b2 + hstep, voffB); PG8_STAGE(PG8_SA(0, 0), a2, voffA);
;             PG8_WAIT_V(8); PG8_WAIT_L(0); PG8_BAR; PG8_MMA(1, 0, At, B0); PG8_MMA(1, 1, At, B1); PG8_BAR; PG8_SCHED;
;             PG8_LDB(B0, 1, 0); PG8_LDB(B1, 1, 1); PG8_SCHED; PG8_LDA(At, 1, 0); PG8_STAGE(PG8_SA(0, 1), a2 + hstep, voffA);
;             PG8_WAIT_V(8); PG8_WAIT_L(0); PG8_BAR; PG8_MMA(0, 0, At, B0); PG8_MMA(0, 1, At, B1); PG8_BAR; PG8_SCHED;
;             PG8_LDA(At, 1, 1); PG8_STAGE(PG8_SB(1, 0), b3, voffB); PG8_STAGE(PG8_SB(1, 1), b3 + hstep, voffB); PG8_STAGE(PG8_SA(1, 0), a3, voffA);
;             PG8_WAIT_V(8); PG8_WAIT_L(0); PG8_BAR; PG8_MMA(1, 0, At, B0); PG8_MMA(1, 1, At, B1); PG8_BAR; PG8_SCHED;
	s_add_i32 s34, s57, s37
	v_lshl_add_u64 v[164:165], v[164:165], 0, s[18:19]
	s_mov_b32 m0, s34
	ds_read_b128 v[190:193], v170 offset:49152
	ds_read_b128 v[194:197], v170 offset:50176
	ds_read_b128 v[198:201], v170 offset:51200
	ds_read_b128 v[202:205], v170 offset:52224
	ds_read_b128 v[206:209], v170 offset:53248
	ds_read_b128 v[210:213], v170 offset:54272
	ds_read_b128 v[214:217], v170 offset:55296
	ds_read_b128 v[218:221], v170 offset:56320
	global_load_lds_dwordx4 v[164:165], off
	s_add_i32 m0, s34, 0x2000
	s_add_u32 s30, s30, 0x100080
	v_lshl_add_u64 v[164:165], v[222:223], 0, s[18:19]
	s_addc_u32 s31, s31, 0
	s_add_i32 s34, s58, s37
	global_load_lds_dwordx4 v[164:165], off
	v_lshl_add_u64 v[164:165], s[30:31], 0, v[134:135]
	s_mov_b32 m0, s34
	s_nop 0
	global_load_lds_dwordx4 v[164:165], off
	v_lshl_add_u64 v[164:165], s[30:31], 0, v[130:131]
	s_add_i32 m0, s34, 0x2000
	s_nop 0
	global_load_lds_dwordx4 v[164:165], off
	v_lshl_add_u64 v[164:165], v[224:225], 0, s[18:19]
	s_mov_b32 m0, s45
	s_nop 0
	global_load_lds_dwordx4 v[164:165], off
	v_lshl_add_u64 v[164:165], v[226:227], 0, s[18:19]
	s_mov_b32 m0, s46
	s_nop 0
	global_load_lds_dwordx4 v[164:165], off
	s_waitcnt vmcnt(8)
	s_waitcnt lgkmcnt(0)
	s_barrier
	s_setprio 1
	s_waitcnt lgkmcnt(0)
	v_mfma_f32_16x16x32_bf16 v[62:65], v[148:151], v[190:193], v[62:65]
	v_mfma_f32_16x16x32_bf16 v[58:61], v[156:159], v[190:193], v[58:61]
	v_mfma_f32_16x16x32_bf16 v[42:45], v[156:159], v[198:201], v[42:45]
	v_mfma_f32_16x16x32_bf16 v[46:49], v[148:151], v[198:201], v[46:49]
	v_mfma_f32_16x16x32_bf16 v[30:33], v[148:151], v[206:209], v[30:33]
	v_mfma_f32_16x16x32_bf16 v[26:29], v[156:159], v[206:209], v[26:29]
	v_mfma_f32_16x16x32_bf16 v[10:13], v[156:159], v[214:217], v[10:13]
	v_mfma_f32_16x16x32_bf16 v[14:17], v[148:151], v[214:217], v[14:17]
	v_mfma_f32_16x16x32_bf16 v[62:65], v[152:155], v[194:197], v[62:65]
	v_mfma_f32_16x16x32_bf16 v[58:61], v[160:163], v[194:197], v[58:61]
	v_mfma_f32_16x16x32_bf16 v[42:45], v[160:163], v[202:205], v[42:45]
	v_mfma_f32_16x16x32_bf16 v[46:49], v[152:155], v[202:205], v[46:49]
	v_mfma_f32_16x16x32_bf16 v[30:33], v[152:155], v[210:213], v[30:33]
	v_mfma_f32_16x16x32_bf16 v[26:29], v[160:163], v[210:213], v[26:29]
	v_mfma_f32_16x16x32_bf16 v[10:13], v[160:163], v[218:221], v[10:13]
	v_mfma_f32_16x16x32_bf16 v[14:17], v[152:155], v[218:221], v[14:17]
	s_setprio 0
	s_setprio 1
	v_mfma_f32_16x16x32_bf16 v[54:57], v[174:177], v[190:193], v[54:57]
	v_mfma_f32_16x16x32_bf16 v[50:53], v[182:185], v[190:193], v[50:53]
	v_mfma_f32_16x16x32_bf16 v[34:37], v[182:185], v[198:201], v[34:37]
	v_mfma_f32_16x16x32_bf16 v[38:41], v[174:177], v[198:201], v[38:41]
	v_mfma_f32_16x16x32_bf16 v[22:25], v[174:177], v[206:209], v[22:25]
	v_mfma_f32_16x16x32_bf16 v[18:21], v[182:185], v[206:209], v[18:21]
	v_mfma_f32_16x16x32_bf16 v[2:5], v[182:185], v[214:217], v[2:5]
	v_mfma_f32_16x16x32_bf16 v[6:9], v[174:177], v[214:217], v[6:9]
	v_mfma_f32_16x16x32_bf16 v[54:57], v[178:181], v[194:197], v[54:57]
	v_mfma_f32_16x16x32_bf16 v[50:53], v[186:189], v[194:197], v[50:53]
	v_mfma_f32_16x16x32_bf16 v[34:37], v[186:189], v[202:205], v[34:37]
	v_mfma_f32_16x16x32_bf16 v[38:41], v[178:181], v[202:205], v[38:41]
	v_mfma_f32_16x16x32_bf16 v[22:25], v[178:181], v[210:213], v[22:25]
	v_mfma_f32_16x16x32_bf16 v[18:21], v[186:189], v[210:213], v[18:21]
	v_mfma_f32_16x16x32_bf16 v[2:5], v[186:189], v[218:221], v[2:5]
	v_mfma_f32_16x16x32_bf16 v[6:9], v[178:181], v[218:221], v[6:9]
	s_setprio 0
	s_barrier
	s_add_i32 s56, s56, 2
	s_add_u32 s4, s4, 0x100
	s_addc_u32 s5, s5, 0
	s_add_u32 s54, s54, 0x100
	s_addc_u32 s55, s55, 0
	s_cmp_gt_u32 s56, 61
	s_cbranch_scc0 .LBB0_1810
	s_and_b64 vcc, exec, s[20:21]
	s_cbranch_vccz .LBB0_1813
	s_barrier
